# P7 and P10 LDS table setup: all 12/32 adaLN and gain loads in flight at once instead of vectorised-by-2 loops with a wait per pair
# speedup vs baseline: 1.0375x; 1.0039x over previous
; __device__ __forceinline__ void p7_rows(const Params& P, LAS unsigned char* lds, int G) {
;     ...
;     for (int idx = tid; idx < 2 * DM; idx += NTHREADS) { const int b = idx >> 11, col = idx & (DM - 1); const float* ab = ada + (size_t)b * NADA;
;         TA[idx] = ab[2 * DM + col] * P.g_post_mix[col]; TB[idx] = P.g_pre_ffn[col] * (1.0f + ab[4 * DM + col]); TC[idx] = ab[3 * DM + col]; }
.LBB0_791:
	s_or_b64 exec, exec, s[0:1]
	s_waitcnt lgkmcnt(0)
	v_mov_b32_e32 v0, v168
	s_movk_i32 s0, 0x1000
	s_barrier
	s_nop 0
	v_cmp_gt_i32_e32 vcc, s0, v0
	s_and_saveexec_b64 s[22:23], vcc
	s_cbranch_execz .LBB0_801
	v_lshlrev_b32_e32 v1, 2, v0
	v_readlane_b32 s4, v241, 16
	v_readlane_b32 s5, v241, 17
	s_nop 1
	s_add_u32 s8, s72, 0x0
	s_addc_u32 s9, s73, 0
	global_load_dword v20, v1, s[8:9]
	s_add_u32 s8, s72, 0x800
	s_addc_u32 s9, s73, 0
	global_load_dword v21, v1, s[8:9]
	s_add_u32 s8, s72, 0x1000
	s_addc_u32 s9, s73, 0
	global_load_dword v22, v1, s[8:9]
	s_add_u32 s8, s72, 0x1800
	s_addc_u32 s9, s73, 0
	global_load_dword v23, v1, s[8:9]
	s_add_u32 s8, s46, 0x0
	s_addc_u32 s9, s47, 0
	global_load_dword v24, v1, s[8:9]
	s_add_u32 s8, s46, 0x800
	s_addc_u32 s9, s47, 0
	global_load_dword v25, v1, s[8:9]
	s_add_u32 s8, s46, 0x1000
	s_addc_u32 s9, s47, 0
	global_load_dword v26, v1, s[8:9]
	s_add_u32 s8, s46, 0x1800
	s_addc_u32 s9, s47, 0
	global_load_dword v27, v1, s[8:9]
	s_add_u32 s8, s4, 0x4000
	s_addc_u32 s9, s5, 0
	global_load_dword v28, v1, s[8:9]
	s_add_u32 s8, s4, 0x8000
	s_addc_u32 s9, s5, 0
	global_load_dword v36, v1, s[8:9]
	s_add_u32 s8, s4, 0x6000
	s_addc_u32 s9, s5, 0
	global_load_dword v44, v1, s[8:9]
	s_add_u32 s8, s4, 0x4800
	s_addc_u32 s9, s5, 0
	global_load_dword v29, v1, s[8:9]
	s_add_u32 s8, s4, 0x8800
	s_addc_u32 s9, s5, 0
	global_load_dword v37, v1, s[8:9]
	s_add_u32 s8, s4, 0x6800
	s_addc_u32 s9, s5, 0
	global_load_dword v45, v1, s[8:9]
	s_add_u32 s8, s4, 0x5000
	s_addc_u32 s9, s5, 0
	global_load_dword v30, v1, s[8:9]
	s_add_u32 s8, s4, 0x9000
	s_addc_u32 s9, s5, 0
	global_load_dword v38, v1, s[8:9]
	s_add_u32 s8, s4, 0x7000
	s_addc_u32 s9, s5, 0
	global_load_dword v46, v1, s[8:9]
	s_add_u32 s8, s4, 0x5800
	s_addc_u32 s9, s5, 0
	global_load_dword v31, v1, s[8:9]
	s_add_u32 s8, s4, 0x9800
	s_addc_u32 s9, s5, 0
	global_load_dword v39, v1, s[8:9]
	s_add_u32 s8, s4, 0x7800
	s_addc_u32 s9, s5, 0
	global_load_dword v47, v1, s[8:9]
	s_add_u32 s8, s4, 0x10000
	s_addc_u32 s9, s5, 0
	global_load_dword v32, v1, s[8:9]
	s_add_u32 s8, s4, 0x14000
	s_addc_u32 s9, s5, 0
	global_load_dword v40, v1, s[8:9]
	s_add_u32 s8, s4, 0x12000
	s_addc_u32 s9, s5, 0
	global_load_dword v48, v1, s[8:9]
	s_add_u32 s8, s4, 0x10800
	s_addc_u32 s9, s5, 0
	global_load_dword v33, v1, s[8:9]
	s_add_u32 s8, s4, 0x14800
	s_addc_u32 s9, s5, 0
	global_load_dword v41, v1, s[8:9]
	s_add_u32 s8, s4, 0x12800
	s_addc_u32 s9, s5, 0
	global_load_dword v49, v1, s[8:9]
	s_add_u32 s8, s4, 0x11000
	s_addc_u32 s9, s5, 0
	global_load_dword v34, v1, s[8:9]
	s_add_u32 s8, s4, 0x15000
	s_addc_u32 s9, s5, 0
	global_load_dword v42, v1, s[8:9]
	s_add_u32 s8, s4, 0x13000
	s_addc_u32 s9, s5, 0
	global_load_dword v50, v1, s[8:9]
	s_add_u32 s8, s4, 0x11800
	s_addc_u32 s9, s5, 0
	global_load_dword v35, v1, s[8:9]
	s_add_u32 s8, s4, 0x15800
	s_addc_u32 s9, s5, 0
	global_load_dword v43, v1, s[8:9]
	s_add_u32 s8, s4, 0x13800
	s_addc_u32 s9, s5, 0
	global_load_dword v51, v1, s[8:9]
	s_waitcnt vmcnt(0)
	v_mul_f32_e32 v52, v28, v20
	v_add_f32_e32 v53, 1.0, v36
	ds_write_b32 v1, v52
	v_mul_f32_e32 v53, v24, v53
	ds_write_b32 v1, v53 offset:16384
	ds_write_b32 v1, v44 offset:32768
	v_mul_f32_e32 v54, v29, v21
	v_add_f32_e32 v55, 1.0, v37
	ds_write_b32 v1, v54 offset:2048
	v_mul_f32_e32 v55, v25, v55
	ds_write_b32 v1, v55 offset:18432
	ds_write_b32 v1, v45 offset:34816
	v_mul_f32_e32 v56, v30, v22
	v_add_f32_e32 v57, 1.0, v38
	ds_write_b32 v1, v56 offset:4096
	v_mul_f32_e32 v57, v26, v57
	ds_write_b32 v1, v57 offset:20480
	ds_write_b32 v1, v46 offset:36864
	v_mul_f32_e32 v58, v31, v23
	v_add_f32_e32 v59, 1.0, v39
	ds_write_b32 v1, v58 offset:6144
	v_mul_f32_e32 v59, v27, v59
	ds_write_b32 v1, v59 offset:22528
	ds_write_b32 v1, v47 offset:38912
	v_mul_f32_e32 v60, v32, v20
	v_add_f32_e32 v61, 1.0, v40
	ds_write_b32 v1, v60 offset:8192
	v_mul_f32_e32 v61, v24, v61
	ds_write_b32 v1, v61 offset:24576
	ds_write_b32 v1, v48 offset:40960
	v_mul_f32_e32 v62, v33, v21
	v_add_f32_e32 v63, 1.0, v41
	ds_write_b32 v1, v62 offset:10240
	v_mul_f32_e32 v63, v25, v63
	ds_write_b32 v1, v63 offset:26624
	ds_write_b32 v1, v49 offset:43008
	v_mul_f32_e32 v64, v34, v22
	v_add_f32_e32 v65, 1.0, v42
	ds_write_b32 v1, v64 offset:12288
	v_mul_f32_e32 v65, v26, v65
	ds_write_b32 v1, v65 offset:28672
	ds_write_b32 v1, v50 offset:45056
	v_mul_f32_e32 v66, v35, v23
	v_add_f32_e32 v67, 1.0, v43
	ds_write_b32 v1, v66 offset:14336
	v_mul_f32_e32 v67, v27, v67
	ds_write_b32 v1, v67 offset:30720
	ds_write_b32 v1, v51 offset:47104

; __device__ __forceinline__ void p10_rows(const Params& P, LAS unsigned char* lds, int G) {
;     ...
;     for (int idx = tid; idx < 2 * DM; idx += NTHREADS) { const int b = idx >> 11, col = idx & (DM - 1); TA[idx] = ada[(size_t)b * NADA + 5 * DM + col] * P.g_post_ffn[col]; }
.LBB0_1005:
	s_or_b64 exec, exec, s[0:1]
	s_movk_i32 s0, 0x1000
	s_waitcnt lgkmcnt(0)
	s_barrier
	s_nop 0
	v_cmp_gt_i32_e32 vcc, s0, v168
	s_and_saveexec_b64 s[4:5], vcc
	s_cbranch_execz .LBB0_1019
	v_lshlrev_b32_e32 v0, 2, v168
	s_add_u32 s8, s48, 0x0
	s_addc_u32 s9, s49, 0
	global_load_dword v10, v0, s[8:9]
	s_add_u32 s8, s48, 0x800
	s_addc_u32 s9, s49, 0
	global_load_dword v11, v0, s[8:9]
	s_add_u32 s8, s48, 0x1000
	s_addc_u32 s9, s49, 0
	global_load_dword v12, v0, s[8:9]
	s_add_u32 s8, s48, 0x1800
	s_addc_u32 s9, s49, 0
	global_load_dword v13, v0, s[8:9]
	s_add_u32 s8, s58, 0x18a000
	s_addc_u32 s9, s59, 0
	global_load_dword v14, v0, s[8:9]
	s_add_u32 s8, s58, 0x18a800
	s_addc_u32 s9, s59, 0
	global_load_dword v15, v0, s[8:9]
	s_add_u32 s8, s58, 0x18b000
	s_addc_u32 s9, s59, 0
	global_load_dword v16, v0, s[8:9]
	s_add_u32 s8, s58, 0x18b800
	s_addc_u32 s9, s59, 0
	global_load_dword v17, v0, s[8:9]
	s_add_u32 s8, s58, 0x196000
	s_addc_u32 s9, s59, 0
	global_load_dword v18, v0, s[8:9]
	s_add_u32 s8, s58, 0x196800
	s_addc_u32 s9, s59, 0
	global_load_dword v19, v0, s[8:9]
	s_add_u32 s8, s58, 0x197000
	s_addc_u32 s9, s59, 0
	global_load_dword v20, v0, s[8:9]
	s_add_u32 s8, s58, 0x197800
	s_addc_u32 s9, s59, 0
	global_load_dword v21, v0, s[8:9]
	s_waitcnt vmcnt(7)
	v_mul_f32_e32 v22, v14, v10
	ds_write_b32 v0, v22
	s_waitcnt vmcnt(6)
	v_mul_f32_e32 v23, v15, v11
	ds_write_b32 v0, v23 offset:2048
	s_waitcnt vmcnt(5)
	v_mul_f32_e32 v24, v16, v12
	ds_write_b32 v0, v24 offset:4096
	s_waitcnt vmcnt(4)
	v_mul_f32_e32 v25, v17, v13
	ds_write_b32 v0, v25 offset:6144
	s_waitcnt vmcnt(3)
	v_mul_f32_e32 v26, v18, v10
	ds_write_b32 v0, v26 offset:8192
	s_waitcnt vmcnt(2)
	v_mul_f32_e32 v27, v19, v11
	ds_write_b32 v0, v27 offset:10240
	s_waitcnt vmcnt(1)
	v_mul_f32_e32 v28, v20, v12
	ds_write_b32 v0, v28 offset:12288
	s_waitcnt vmcnt(0)
	v_mul_f32_e32 v29, v21, v13
	ds_write_b32 v0, v29 offset:14336
